# latent attention: 8 packed v_pk_fma_f32 scale-and-shift ops split into scalar v_fmamk_f32 pairs (packed f32 issues slower beside MFMAs); 5 NaN-canonicalising self-max ops per tile folded into the max
# baseline (speedup 1.0000x reference)
.LBB0_709:
	s_add_i32 s20, s85, -3
	ds_read_b128 v[64:67], v204 offset:49152
	ds_read_b128 v[68:71], v204 offset:57344
	ds_read_b128 v[178:181], v207 offset:49152
	ds_read_b128 v[182:185], v207 offset:57344
	v_exp_f32_e32 v144, v158
	v_exp_f32_e32 v158, v159
	s_waitcnt lgkmcnt(3)
	v_mfma_f32_32x32x16_bf16 v[80:95], v[64:67], v[124:127], 0
	v_exp_f32_e32 v159, v160
	v_add_f32_e32 v160, 0, v216
	v_add_f32_e32 v160, v230, v160
	v_add_f32_e32 v160, v174, v160
	v_add_f32_e32 v160, v219, v160
	v_add_f32_e32 v160, v173, v160
	v_add_f32_e32 v160, v175, v160
	s_waitcnt lgkmcnt(2)
	v_mfma_f32_32x32x16_bf16 v[64:79], v[68:71], v[124:127], 0
	v_add_f32_e32 v160, v163, v160
	v_add_f32_e32 v160, v172, v160
	v_add_f32_e32 v160, v164, v160
	v_add_f32_e32 v160, v171, v160
	v_add_f32_e32 v160, v165, v160
	v_add_f32_e32 v160, v170, v160
	v_add_f32_e32 v160, v166, v160
	s_waitcnt lgkmcnt(1)
	v_mfma_f32_32x32x16_bf16 v[80:95], v[178:181], v[120:123], v[80:95]
	v_add_f32_e32 v160, v169, v160
	v_exp_f32_e32 v156, v156
	v_add_f32_e32 v160, v145, v160
	v_exp_f32_e32 v157, v157
	v_add_f32_e32 v160, v167, v160
	v_exp_f32_e32 v150, v150
	v_add_f32_e32 v160, v144, v160
	s_waitcnt lgkmcnt(0)
	v_mfma_f32_32x32x16_bf16 v[64:79], v[182:185], v[120:123], v[64:79]
	ds_read_b128 v[178:181], v209 offset:49152
	ds_read_b128 v[182:185], v209 offset:57344
	v_exp_f32_e32 v151, v151
	v_add_f32_e32 v160, v158, v160
	v_exp_f32_e32 v148, v148
	v_add_f32_e32 v160, v156, v160
	v_exp_f32_e32 v149, v149
	v_add_f32_e32 v160, v157, v160
	s_waitcnt lgkmcnt(1)
	v_mfma_f32_32x32x16_bf16 v[80:95], v[178:181], v[116:119], v[80:95]
	v_exp_f32_e32 v146, v146
	v_add_f32_e32 v160, v150, v160
	v_exp_f32_e32 v147, v147
	v_add_f32_e32 v160, v151, v160
	v_add_f32_e32 v160, v148, v160
	v_add_f32_e32 v160, v149, v160
	v_exp_f32_e32 v154, v154
	s_waitcnt lgkmcnt(0)
	v_mfma_f32_32x32x16_bf16 v[64:79], v[182:185], v[116:119], v[64:79]
	ds_read_b128 v[178:181], v205 offset:49152
	ds_read_b128 v[182:185], v205 offset:57344
	v_add_f32_e32 v160, v146, v160
	v_exp_f32_e32 v155, v155
	v_add_f32_e32 v160, v147, v160
	v_exp_f32_e32 v152, v152
	v_add_f32_e32 v160, v159, v160
	v_exp_f32_e32 v153, v153
	s_waitcnt lgkmcnt(1)
	v_mfma_f32_32x32x16_bf16 v[80:95], v[178:181], v[112:115], v[80:95]
	s_waitcnt lgkmcnt(0)
	v_mfma_f32_32x32x16_bf16 v[64:79], v[182:185], v[112:115], v[64:79]
	ds_read_b128 v[178:181], v206 offset:49152
	ds_read_b128 v[182:185], v206 offset:57344
	s_waitcnt lgkmcnt(1)
	v_mfma_f32_32x32x16_bf16 v[80:95], v[178:181], v[108:111], v[80:95]
	s_waitcnt lgkmcnt(0)
	v_mfma_f32_32x32x16_bf16 v[64:79], v[182:185], v[108:111], v[64:79]
	ds_read_b128 v[178:181], v208 offset:49152
	ds_read_b128 v[182:185], v208 offset:57344
	s_waitcnt lgkmcnt(1)
	v_mfma_f32_32x32x16_bf16 v[80:95], v[178:181], v[104:107], v[80:95]
	s_waitcnt lgkmcnt(0)
	v_mfma_f32_32x32x16_bf16 v[64:79], v[182:185], v[104:107], v[64:79]
	ds_read_b128 v[178:181], v210 offset:49152
	ds_read_b128 v[182:185], v210 offset:57344
	s_waitcnt lgkmcnt(1)
	v_mfma_f32_32x32x16_bf16 v[80:95], v[178:181], v[100:103], v[80:95]
	s_waitcnt lgkmcnt(0)
	v_mfma_f32_32x32x16_bf16 v[64:79], v[182:185], v[100:103], v[64:79]
	ds_read_b128 v[178:181], v211 offset:49152
	ds_read_b128 v[182:185], v211 offset:57344
	s_waitcnt lgkmcnt(1)
	v_mfma_f32_32x32x16_bf16 v[80:95], v[178:181], v[96:99], v[80:95]
	v_exp_f32_e32 v179, v161
	s_nop 0
	v_add_f32_e32 v160, v179, v160
	v_add_f32_e32 v160, v154, v160
	v_add_f32_e32 v160, v155, v160
	s_waitcnt lgkmcnt(0)
	v_mfma_f32_32x32x16_bf16 v[64:79], v[182:185], v[96:99], v[64:79]
	v_add_f32_e32 v160, v152, v160
	v_add_f32_e32 v213, v153, v160
	v_mov_b32_e32 v214, v213
	v_cvt_pk_bf16_f32 v160, v216, v230
	v_cvt_pk_bf16_f32 v161, v174, v219
	v_cvt_pk_bf16_f32 v162, v173, v175
	s_nop 1
	v_permlane32_swap_b32_e32 v213, v214
	v_cvt_pk_bf16_f32 v163, v163, v172
	v_permlane32_swap_b32_e32 v160, v162
	v_cvt_pk_bf16_f32 v164, v164, v171
	v_cvt_pk_bf16_f32 v165, v165, v170
	v_cvt_pk_bf16_f32 v166, v166, v169
	v_cvt_pk_bf16_f32 v167, v145, v167
	v_cvt_pk_bf16_f32 v170, v144, v158
	v_cvt_pk_bf16_f32 v171, v156, v157
	v_cvt_pk_bf16_f32 v172, v150, v151
	v_cvt_pk_bf16_f32 v173, v148, v149
	v_cvt_pk_bf16_f32 v178, v146, v147
	v_cvt_pk_bf16_f32 v179, v159, v179
	v_cvt_pk_bf16_f32 v180, v154, v155
	v_cvt_pk_bf16_f32 v181, v152, v153
	v_permlane32_swap_b32_e32 v161, v163
	v_permlane32_swap_b32_e32 v164, v166
	v_permlane32_swap_b32_e32 v165, v167
	v_permlane32_swap_b32_e32 v170, v172
	v_permlane32_swap_b32_e32 v171, v173
	v_permlane32_swap_b32_e32 v178, v180
	v_permlane32_swap_b32_e32 v179, v181
	s_cmp_lt_u32 s20, 6
	s_cselect_b64 s[4:5], -1, 0
	s_and_b64 s[18:19], s[4:5], exec
	s_cselect_b32 s16, 0, -8
	s_add_i32 s16, s16, s85
	s_add_i32 s16, s16, -1
	s_and_b64 s[4:5], s[4:5], exec
	s_cselect_b32 s19, s49, s43
	s_cselect_b32 s18, s48, s36
	s_cselect_b32 s21, s57, s52
	s_cselect_b32 s22, s56, s44
	s_lshl_b64 s[4:5], s[16:17], 16
	s_add_u32 s18, s18, s4
	s_addc_u32 s19, s19, s5
	s_add_u32 s4, s22, s4
	s_addc_u32 s5, s21, s5
	global_load_dwordx4 v[144:147], v222, s[4:5]
	global_load_dwordx4 v[148:151], v243, s[4:5]
	global_load_dwordx4 v[152:155], v222, s[18:19]
	global_load_dwordx4 v[156:159], v243, s[18:19]
	ds_read_b64_tr_b16 v[182:183], v199 offset:0
	ds_read_b64_tr_b16 v[184:185], v199 offset:0x800
	ds_read_b64_tr_b16 v[216:217], v199 offset:0x1000
	ds_read_b64_tr_b16 v[218:219], v199 offset:0x1800
	ds_read_b64_tr_b16 v[230:231], v199 offset:0x2000
	ds_read_b64_tr_b16 v[232:233], v199 offset:0x2800
	ds_read_b64_tr_b16 v[234:235], v199 offset:0x3000
	ds_read_b64_tr_b16 v[236:237], v199 offset:0x3800
	s_waitcnt lgkmcnt(0)
	s_nop 0
	v_mfma_f32_32x32x16_bf16 v[0:15], v[160:163], v[182:185], v[0:15]
	ds_read_b64_tr_b16 v[182:183], v199 offset:0x200
	ds_read_b64_tr_b16 v[184:185], v199 offset:0xa00
	v_mfma_f32_32x32x16_bf16 v[0:15], v[164:167], v[216:219], v[0:15]
	ds_read_b64_tr_b16 v[216:217], v199 offset:0x1200
	ds_read_b64_tr_b16 v[218:219], v199 offset:0x1a00
	v_mfma_f32_32x32x16_bf16 v[0:15], v[170:173], v[230:233], v[0:15]
	ds_read_b64_tr_b16 v[230:231], v199 offset:0x2200
	ds_read_b64_tr_b16 v[232:233], v199 offset:0x2a00
	v_mfma_f32_32x32x16_bf16 v[0:15], v[178:181], v[234:237], v[0:15]
	ds_read_b64_tr_b16 v[234:235], v199 offset:0x3200
	ds_read_b64_tr_b16 v[236:237], v199 offset:0x3a00
	s_waitcnt lgkmcnt(0)
	v_mfma_f32_32x32x16_bf16 v[48:63], v[160:163], v[182:185], v[48:63]
	ds_read_b64_tr_b16 v[182:183], v199 offset:0x400
	ds_read_b64_tr_b16 v[184:185], v199 offset:0xc00
	v_mfma_f32_32x32x16_bf16 v[48:63], v[164:167], v[216:219], v[48:63]
	ds_read_b64_tr_b16 v[216:217], v199 offset:0x1400
	ds_read_b64_tr_b16 v[218:219], v199 offset:0x1c00
	v_mfma_f32_32x32x16_bf16 v[48:63], v[170:173], v[230:233], v[48:63]
	ds_read_b64_tr_b16 v[230:231], v199 offset:0x2400
	ds_read_b64_tr_b16 v[232:233], v199 offset:0x2c00
	v_mfma_f32_32x32x16_bf16 v[48:63], v[178:181], v[234:237], v[48:63]
	ds_read_b64_tr_b16 v[234:235], v199 offset:0x3400
	ds_read_b64_tr_b16 v[236:237], v199 offset:0x3c00
	s_waitcnt lgkmcnt(0)
	v_mfma_f32_32x32x16_bf16 v[32:47], v[160:163], v[182:185], v[32:47]
	ds_read_b64_tr_b16 v[182:183], v199 offset:0x600
	ds_read_b64_tr_b16 v[184:185], v199 offset:0xe00
	v_mfma_f32_32x32x16_bf16 v[32:47], v[164:167], v[216:219], v[32:47]
	ds_read_b64_tr_b16 v[216:217], v199 offset:0x1600
	ds_read_b64_tr_b16 v[218:219], v199 offset:0x1e00
	v_mfma_f32_32x32x16_bf16 v[32:47], v[170:173], v[230:233], v[32:47]
	ds_read_b64_tr_b16 v[230:231], v199 offset:0x2600
	ds_read_b64_tr_b16 v[232:233], v199 offset:0x2e00
	v_mfma_f32_32x32x16_bf16 v[32:47], v[178:181], v[234:237], v[32:47]
	ds_read_b64_tr_b16 v[234:235], v199 offset:0x3600
	ds_read_b64_tr_b16 v[236:237], v199 offset:0x3e00
	s_waitcnt lgkmcnt(0)
	v_mfma_f32_32x32x16_bf16 v[16:31], v[160:163], v[182:185], v[16:31]
	v_max_f32_e32 v160, v81, v80
	v_max3_f32 v160, v160, v82, v83
	v_max3_f32 v160, v160, v84, v85
	v_max3_f32 v160, v160, v86, v87
	v_max3_f32 v160, v160, v88, v89
	v_max3_f32 v160, v160, v90, v91
	v_max3_f32 v160, v160, v92, v93
	v_mfma_f32_32x32x16_bf16 v[16:31], v[164:167], v[216:219], v[16:31]
	v_max3_f32 v160, v160, v94, v95
	v_max3_f32 v160, v160, v64, v65
	v_max3_f32 v160, v160, v66, v67
	v_max3_f32 v160, v160, v68, v69
	v_max3_f32 v160, v160, v70, v71
	v_max3_f32 v160, v160, v72, v73
	v_max3_f32 v160, v160, v74, v75
	v_max3_f32 v160, v160, v76, v77
	v_mfma_f32_32x32x16_bf16 v[16:31], v[170:173], v[230:233], v[16:31]
	v_max3_f32 v160, v160, v78, v79
	v_mov_b32_e32 v161, v160
	s_nop 1
	v_permlane32_swap_b32_e32 v160, v161
	v_max_f32_e32 v160, v161, v160
	v_sub_f32_e32 v161, v160, v168
	v_cmp_ge_f32_e32 vcc, s14, v161
	v_max_f32_e32 v160, v168, v160
	v_mfma_f32_32x32x16_bf16 v[16:31], v[178:181], v[234:237], v[16:31]
	v_sub_f32_e32 v161, v168, v160
	v_mul_f32_e32 v161, 0x3e0293ee, v161
	v_exp_f32_e32 v161, v161
	s_cmp_eq_u64 vcc, exec
	s_cselect_b64 s[4:5], -1, 0
	s_barrier
	s_waitcnt vmcnt(4)
	v_cndmask_b32_e64 v215, v161, 1.0, s[4:5]
	v_cmp_gt_f32_e32 vcc, 1.0, v215
	s_waitcnt vmcnt(4)
	ds_write_b128 v200, v[128:131]
	ds_write_b128 v201, v[132:135]
	ds_write_b128 v202, v[136:139] offset:32768
	ds_write_b128 v203, v[140:143] offset:32768
	s_cbranch_vccz .LBB0_713
	s_and_saveexec_b64 s[18:19], s[2:3]
	ds_write_b32 v189, v215 offset:128
	s_or_b64 exec, exec, s[18:19]
	s_waitcnt lgkmcnt(0)
	v_add_u32_e32 v161, v191, v190
	ds_read_b128 v[162:165], v161 offset:224
	ds_read_b128 v[170:173], v161 offset:192
	ds_read_b128 v[178:181], v161 offset:160
	ds_read_b128 v[182:185], v161 offset:128
	s_waitcnt lgkmcnt(3)
	v_pk_mul_f32 v[12:13], v[12:13], v[162:163]
	s_waitcnt lgkmcnt(2)
	v_pk_mul_f32 v[8:9], v[8:9], v[170:171]
	s_waitcnt lgkmcnt(1)
	v_pk_mul_f32 v[4:5], v[4:5], v[178:179]
	v_pk_mul_f32 v[14:15], v[14:15], v[164:165]
	v_pk_mul_f32 v[10:11], v[10:11], v[172:173]
	v_pk_mul_f32 v[6:7], v[6:7], v[180:181]
	s_waitcnt lgkmcnt(0)
	v_pk_mul_f32 v[2:3], v[2:3], v[184:185]
	v_pk_mul_f32 v[0:1], v[0:1], v[182:183]
	v_pk_mul_f32 v[60:61], v[60:61], v[162:163]
	v_pk_mul_f32 v[56:57], v[56:57], v[170:171]
	v_pk_mul_f32 v[52:53], v[52:53], v[178:179]
	v_pk_mul_f32 v[62:63], v[62:63], v[164:165]
	v_pk_mul_f32 v[58:59], v[58:59], v[172:173]
	v_pk_mul_f32 v[54:55], v[54:55], v[180:181]
	v_pk_mul_f32 v[50:51], v[50:51], v[184:185]
	v_pk_mul_f32 v[48:49], v[48:49], v[182:183]
	v_pk_mul_f32 v[44:45], v[44:45], v[162:163]
	v_pk_mul_f32 v[40:41], v[40:41], v[170:171]
	v_pk_mul_f32 v[36:37], v[36:37], v[178:179]
	v_pk_mul_f32 v[46:47], v[46:47], v[164:165]
	v_pk_mul_f32 v[42:43], v[42:43], v[172:173]
	v_pk_mul_f32 v[38:39], v[38:39], v[180:181]
	v_pk_mul_f32 v[34:35], v[34:35], v[184:185]
	v_pk_mul_f32 v[32:33], v[32:33], v[182:183]
	v_pk_mul_f32 v[28:29], v[28:29], v[162:163]
	v_pk_mul_f32 v[24:25], v[24:25], v[170:171]
	v_pk_mul_f32 v[20:21], v[20:21], v[178:179]
	v_pk_mul_f32 v[30:31], v[30:31], v[164:165]
	v_pk_mul_f32 v[26:27], v[26:27], v[172:173]
	v_pk_mul_f32 v[22:23], v[22:23], v[180:181]
	v_pk_mul_f32 v[18:19], v[18:19], v[184:185]
	v_pk_mul_f32 v[16:17], v[16:17], v[182:183]

.LBB0_715:
	ds_read_b64_tr_b16 v[178:179], v198 offset:0
	ds_read_b64_tr_b16 v[180:181], v198 offset:0x800
	ds_read_b64_tr_b16 v[182:183], v198 offset:0x1000
	ds_read_b64_tr_b16 v[184:185], v198 offset:0x1800
	ds_read_b64_tr_b16 v[230:231], v198 offset:0x2000
	ds_read_b64_tr_b16 v[232:233], v198 offset:0x2800
	ds_read_b64_tr_b16 v[234:235], v198 offset:0x3000
	ds_read_b64_tr_b16 v[236:237], v198 offset:0x3800
	s_waitcnt lgkmcnt(0)
	s_nop 0
	v_mfma_f32_32x32x16_bf16 v[0:15], v[160:163], v[178:181], v[0:15]
	ds_read_b64_tr_b16 v[178:179], v198 offset:0x200
	ds_read_b64_tr_b16 v[180:181], v198 offset:0xa00
	v_mfma_f32_32x32x16_bf16 v[0:15], v[164:167], v[182:185], v[0:15]
	ds_read_b64_tr_b16 v[182:183], v198 offset:0x1200
	ds_read_b64_tr_b16 v[184:185], v198 offset:0x1a00
	v_mfma_f32_32x32x16_bf16 v[0:15], v[168:171], v[230:233], v[0:15]
	ds_read_b64_tr_b16 v[230:231], v198 offset:0x2200
	ds_read_b64_tr_b16 v[232:233], v198 offset:0x2a00
	v_mfma_f32_32x32x16_bf16 v[0:15], v[172:175], v[234:237], v[0:15]
	ds_read_b64_tr_b16 v[234:235], v198 offset:0x3200
	ds_read_b64_tr_b16 v[236:237], v198 offset:0x3a00
	s_waitcnt lgkmcnt(0)
	v_mfma_f32_32x32x16_bf16 v[48:63], v[160:163], v[178:181], v[48:63]
	ds_read_b64_tr_b16 v[178:179], v198 offset:0x400
	ds_read_b64_tr_b16 v[180:181], v198 offset:0xc00
	v_mfma_f32_32x32x16_bf16 v[48:63], v[164:167], v[182:185], v[48:63]
	ds_read_b64_tr_b16 v[182:183], v198 offset:0x1400
	ds_read_b64_tr_b16 v[184:185], v198 offset:0x1c00
	v_mfma_f32_32x32x16_bf16 v[48:63], v[168:171], v[230:233], v[48:63]
	ds_read_b64_tr_b16 v[230:231], v198 offset:0x2400
	ds_read_b64_tr_b16 v[232:233], v198 offset:0x2c00
	v_mfma_f32_32x32x16_bf16 v[48:63], v[172:175], v[234:237], v[48:63]
	ds_read_b64_tr_b16 v[234:235], v198 offset:0x3400
	ds_read_b64_tr_b16 v[236:237], v198 offset:0x3c00
	s_waitcnt lgkmcnt(0)
	v_mfma_f32_32x32x16_bf16 v[32:47], v[160:163], v[178:181], v[32:47]
	ds_read_b64_tr_b16 v[178:179], v198 offset:0x600
	ds_read_b64_tr_b16 v[180:181], v198 offset:0xe00
	v_mfma_f32_32x32x16_bf16 v[32:47], v[164:167], v[182:185], v[32:47]
	ds_read_b64_tr_b16 v[182:183], v198 offset:0x1600
	ds_read_b64_tr_b16 v[184:185], v198 offset:0x1e00
	v_mfma_f32_32x32x16_bf16 v[32:47], v[168:171], v[230:233], v[32:47]
	ds_read_b64_tr_b16 v[230:231], v198 offset:0x2600
	ds_read_b64_tr_b16 v[232:233], v198 offset:0x2e00
	v_mfma_f32_32x32x16_bf16 v[32:47], v[172:175], v[234:237], v[32:47]
	ds_read_b64_tr_b16 v[234:235], v198 offset:0x3600
	ds_read_b64_tr_b16 v[236:237], v198 offset:0x3e00
	s_waitcnt lgkmcnt(0)
	v_mfma_f32_32x32x16_bf16 v[16:31], v[160:163], v[178:181], v[16:31]
	v_max_f32_e32 v160, v81, v80
	v_max3_f32 v160, v160, v82, v83
	v_max3_f32 v160, v160, v84, v85
	v_max3_f32 v160, v160, v86, v87
	v_max3_f32 v160, v160, v88, v89
	v_max3_f32 v160, v160, v90, v91
	v_max3_f32 v160, v160, v92, v93
	v_mfma_f32_32x32x16_bf16 v[16:31], v[164:167], v[182:185], v[16:31]
	v_max3_f32 v160, v160, v94, v95
	v_max3_f32 v160, v160, v64, v65
	v_max3_f32 v160, v160, v66, v67
	v_max3_f32 v160, v160, v68, v69
	v_max3_f32 v160, v160, v70, v71
	v_max3_f32 v160, v160, v72, v73
	v_max3_f32 v160, v160, v74, v75
	v_max3_f32 v160, v160, v76, v77
	v_mfma_f32_32x32x16_bf16 v[16:31], v[168:171], v[230:233], v[16:31]
	v_max3_f32 v160, v160, v78, v79
	v_mov_b32_e32 v161, v160
	s_nop 1
	v_permlane32_swap_b32_e32 v160, v161
	v_max_f32_e32 v160, v161, v160
	v_sub_f32_e32 v161, v160, v216
	v_cmp_ge_f32_e32 vcc, s14, v161
	v_max_f32_e32 v160, v216, v160
	v_mfma_f32_32x32x16_bf16 v[16:31], v[172:175], v[234:237], v[16:31]
	v_sub_f32_e32 v161, v216, v160
	v_mul_f32_e32 v161, 0x3e0293ee, v161
	v_exp_f32_e32 v161, v161
	s_cmp_eq_u64 vcc, exec
	s_cselect_b64 s[4:5], -1, 0
	s_barrier
	s_waitcnt vmcnt(4)
	v_cndmask_b32_e64 v162, v161, 1.0, s[4:5]
	v_cmp_gt_f32_e32 vcc, 1.0, v162
	s_waitcnt vmcnt(3)
	ds_write_b128 v200, v[144:147] offset:16384
	s_waitcnt vmcnt(2)
	ds_write_b128 v201, v[148:151] offset:16384
	s_waitcnt vmcnt(1)
	ds_write_b128 v202, v[152:155] offset:49152
	s_waitcnt vmcnt(0)
	ds_write_b128 v203, v[156:159] offset:49152
	s_cbranch_vccz .LBB0_719
	s_and_saveexec_b64 s[18:19], s[2:3]
	ds_write_b32 v189, v162 offset:128
	s_or_b64 exec, exec, s[18:19]
	s_waitcnt lgkmcnt(0)
	v_add_u32_e32 v156, v191, v190
	ds_read_b128 v[144:147], v156 offset:224
	ds_read_b128 v[148:151], v156 offset:192
	ds_read_b128 v[152:155], v156 offset:160
	ds_read_b128 v[156:159], v156 offset:128
	s_waitcnt lgkmcnt(3)
	v_pk_mul_f32 v[12:13], v[12:13], v[144:145]
	s_waitcnt lgkmcnt(2)
	v_pk_mul_f32 v[8:9], v[8:9], v[148:149]
	s_waitcnt lgkmcnt(1)
	v_pk_mul_f32 v[4:5], v[4:5], v[152:153]
	v_pk_mul_f32 v[14:15], v[14:15], v[146:147]
	v_pk_mul_f32 v[10:11], v[10:11], v[150:151]
	v_pk_mul_f32 v[6:7], v[6:7], v[154:155]
	s_waitcnt lgkmcnt(0)
	v_pk_mul_f32 v[2:3], v[2:3], v[158:159]
	v_pk_mul_f32 v[0:1], v[0:1], v[156:157]
	v_pk_mul_f32 v[60:61], v[60:61], v[144:145]
	v_pk_mul_f32 v[56:57], v[56:57], v[148:149]
	v_pk_mul_f32 v[52:53], v[52:53], v[152:153]
	v_pk_mul_f32 v[62:63], v[62:63], v[146:147]
	v_pk_mul_f32 v[58:59], v[58:59], v[150:151]
	v_pk_mul_f32 v[54:55], v[54:55], v[154:155]
	v_pk_mul_f32 v[50:51], v[50:51], v[158:159]
	v_pk_mul_f32 v[48:49], v[48:49], v[156:157]
	v_pk_mul_f32 v[44:45], v[44:45], v[144:145]
	v_pk_mul_f32 v[40:41], v[40:41], v[148:149]
	v_pk_mul_f32 v[36:37], v[36:37], v[152:153]
	v_pk_mul_f32 v[46:47], v[46:47], v[146:147]
	v_pk_mul_f32 v[42:43], v[42:43], v[150:151]
	v_pk_mul_f32 v[38:39], v[38:39], v[154:155]
	v_pk_mul_f32 v[34:35], v[34:35], v[158:159]
	v_pk_mul_f32 v[32:33], v[32:33], v[156:157]
	v_pk_mul_f32 v[28:29], v[28:29], v[144:145]
	v_pk_mul_f32 v[24:25], v[24:25], v[148:149]
	v_pk_mul_f32 v[20:21], v[20:21], v[152:153]
	v_pk_mul_f32 v[30:31], v[30:31], v[146:147]
	v_pk_mul_f32 v[26:27], v[26:27], v[150:151]
	v_pk_mul_f32 v[22:23], v[22:23], v[154:155]
	v_pk_mul_f32 v[18:19], v[18:19], v[158:159]
	v_pk_mul_f32 v[16:17], v[16:17], v[156:157]
.LBB0_719:
	v_cndmask_b32_e64 v168, v160, v216, s[4:5]
	v_mul_f32_e32 v144, 0xbe0293ee, v168
	v_fmamk_f32 v94, v94, 0x3e0293ee, v144
	v_mov_b32_e32 v152, v144
	v_fmamk_f32 v80, v80, 0x3e0293ee, v144
	v_fmamk_f32 v81, v81, 0x3e0293ee, v144
	v_fmamk_f32 v82, v82, 0x3e0293ee, v144
	v_fmamk_f32 v83, v83, 0x3e0293ee, v144
	v_fmamk_f32 v84, v84, 0x3e0293ee, v144
	v_fmamk_f32 v85, v85, 0x3e0293ee, v144
	v_fmamk_f32 v86, v86, 0x3e0293ee, v144
	v_fmamk_f32 v87, v87, 0x3e0293ee, v144
	v_fmamk_f32 v88, v88, 0x3e0293ee, v144
	v_fmamk_f32 v89, v89, 0x3e0293ee, v144
	v_fmamk_f32 v90, v90, 0x3e0293ee, v144
	v_fmamk_f32 v91, v91, 0x3e0293ee, v144
	v_fmamk_f32 v92, v92, 0x3e0293ee, v144
	v_fmamk_f32 v93, v93, 0x3e0293ee, v144
	v_fmac_f32_e32 v152, 0x3e0293ee, v95
	v_fmamk_f32 v158, v64, 0x3e0293ee, v144
	v_fmamk_f32 v159, v65, 0x3e0293ee, v144
	v_fmamk_f32 v156, v66, 0x3e0293ee, v144
	v_fmamk_f32 v157, v67, 0x3e0293ee, v144
	v_fmamk_f32 v150, v68, 0x3e0293ee, v144
	v_fmamk_f32 v151, v69, 0x3e0293ee, v144
	v_fmamk_f32 v148, v70, 0x3e0293ee, v144
	v_fmamk_f32 v149, v71, 0x3e0293ee, v144
	v_fmamk_f32 v146, v72, 0x3e0293ee, v144
	v_fmamk_f32 v147, v73, 0x3e0293ee, v144
	v_exp_f32_e32 v145, v94
	v_exp_f32_e32 v216, v80
	v_exp_f32_e32 v230, v81
	v_exp_f32_e32 v174, v82
	v_exp_f32_e32 v219, v83
	v_exp_f32_e32 v173, v84
	v_exp_f32_e32 v175, v85
	v_exp_f32_e32 v163, v86
	v_exp_f32_e32 v172, v87
	v_exp_f32_e32 v164, v88
	v_exp_f32_e32 v171, v89
	v_exp_f32_e32 v165, v90
	v_exp_f32_e32 v170, v91
	v_exp_f32_e32 v166, v92
	v_exp_f32_e32 v169, v93
	v_exp_f32_e32 v167, v152
	v_add_f32_e32 v64, v213, v214
	v_fmac_f32_e32 v64, v212, v197
	v_add_f32_e32 v197, v217, v218
	s_add_i32 s85, s85, 2
	v_fmamk_f32 v160, v74, 0x3e0293ee, v144
	v_fmamk_f32 v161, v75, 0x3e0293ee, v144
	v_fmamk_f32 v154, v76, 0x3e0293ee, v144
	v_fmamk_f32 v155, v77, 0x3e0293ee, v144
	v_fmamk_f32 v152, v78, 0x3e0293ee, v144
	v_fmamk_f32 v153, v79, 0x3e0293ee, v144
	v_fmac_f32_e32 v197, v64, v215
	s_cmpk_gt_u32 s20, 0x44
	s_waitcnt lgkmcnt(0)
	s_barrier
	s_cbranch_scc1 .LBB0_721
	v_mov_b32_e32 v212, v162
	s_branch .LBB0_709
